# attention epilogues (diff + stick-breaking): the wave's 32x128 bf16 tile goes through a private LDS slab and is stored with 8 row-contiguous dwordx4 stores instead of 64 2-byte stores per lane (asm gu
# speedup vs baseline: 1.0022x; 1.0022x over previous
; __device__ __forceinline__ float bf_lo(unsigned u) { return __uint_as_float(u << 16); }
; __device__ __forceinline__ float bf_hi(unsigned u) { return __uint_as_float(u & 0xffff0000u); }
; __device__ __forceinline__ int crow(int r, int h) { return (r & 3) + 8 * (r >> 2) + 4 * h; }
; __device__ __forceinline__ void diff_unit(const Params& p, LAS unsigned char* lds, int b, int h, int qb, float lam) {
;     ...
;         for (int r = 0; r < 16; ++r) { const float a = (mp == 0 ? 1.0f : lam) / L[r];
; #pragma unroll
;             for (int db = 0; db < 4; ++db) O[db][r] *= a; }
;     ...
;     for (int r = 0; r < 16; ++r) {
;         const int qr = crow(r, hh);
;         float o[4]; float ss = 0.f;
; #pragma unroll
;         for (int db = 0; db < 4; ++db) { const unsigned w = park[(db * 8 + (r >> 1)) * 64]; o[db] = ((r & 1) ? bf_hi(w) : bf_lo(w)) - O[db][r]; ss += o[db] * o[db]; }
.LBB0_267:
	s_nop 11
	s_waitcnt vmcnt(0)
	s_barrier
	s_mov_b64 s[0:1], 0x1000
	v_lshl_add_u64 v[14:15], v[164:165], 0, s[0:1]
	global_load_dword v136, v[164:165], off
	global_load_dword v137, v[164:165], off offset:256
	global_load_dword v138, v[164:165], off offset:512
	global_load_dword v139, v[164:165], off offset:768
	global_load_dword v140, v[164:165], off offset:1024
	global_load_dword v141, v[164:165], off offset:1280
	global_load_dword v142, v[164:165], off offset:1536
	global_load_dword v143, v[164:165], off offset:1792
	global_load_dword v144, v[164:165], off offset:2048
	global_load_dword v145, v[164:165], off offset:2304
	global_load_dword v146, v[164:165], off offset:2560
	global_load_dword v147, v[164:165], off offset:2816
	global_load_dword v148, v[164:165], off offset:3072
	global_load_dword v149, v[164:165], off offset:3328
	global_load_dword v150, v[164:165], off offset:3584
	global_load_dword v151, v[164:165], off offset:3840
	global_load_dword v152, v[14:15], off
	global_load_dword v153, v[14:15], off offset:256
	global_load_dword v154, v[14:15], off offset:512
	global_load_dword v155, v[14:15], off offset:768
	global_load_dword v156, v[14:15], off offset:1024
	global_load_dword v157, v[14:15], off offset:1280
	global_load_dword v158, v[14:15], off offset:1536
	global_load_dword v159, v[14:15], off offset:1792
	global_load_dword v176, v[14:15], off offset:2048
	global_load_dword v177, v[14:15], off offset:2304
	global_load_dword v178, v[14:15], off offset:2560
	global_load_dword v179, v[14:15], off offset:2816
	global_load_dword v180, v[14:15], off offset:3072
	global_load_dword v181, v[14:15], off offset:3328
	global_load_dword v182, v[14:15], off offset:3584
	global_load_dword v183, v[14:15], off offset:3840
	v_div_scale_f32 v2, s[0:1], v80, v80, v161
	v_rcp_f32_e32 v3, v2
	v_div_scale_f32 v4, vcc, v161, v80, v161
	v_fma_f32 v5, -v2, v3, 1.0
	v_fmac_f32_e32 v3, v5, v3
	v_mul_f32_e32 v5, v4, v3
	v_fma_f32 v6, -v2, v5, v4
	v_fmac_f32_e32 v5, v6, v3
	v_fma_f32 v2, -v2, v5, v4
	v_div_fmas_f32 v2, v2, v3, v5
	v_div_fixup_f32 v112, v2, v80, v161
	v_div_scale_f32 v2, s[0:1], v81, v81, v161
	v_rcp_f32_e32 v3, v2
	v_div_scale_f32 v4, vcc, v161, v81, v161
	v_fma_f32 v5, -v2, v3, 1.0
	v_fmac_f32_e32 v3, v5, v3
	v_mul_f32_e32 v5, v4, v3
	v_fma_f32 v6, -v2, v5, v4
	v_fmac_f32_e32 v5, v6, v3
	v_fma_f32 v2, -v2, v5, v4
	v_div_fmas_f32 v2, v2, v3, v5
	v_div_fixup_f32 v113, v2, v81, v161
	v_div_scale_f32 v2, s[0:1], v82, v82, v161
	v_rcp_f32_e32 v3, v2
	v_div_scale_f32 v4, vcc, v161, v82, v161
	v_fma_f32 v5, -v2, v3, 1.0
	v_fmac_f32_e32 v3, v5, v3
	v_mul_f32_e32 v5, v4, v3
	v_fma_f32 v6, -v2, v5, v4
	v_fmac_f32_e32 v5, v6, v3
	v_fma_f32 v2, -v2, v5, v4
	v_div_fmas_f32 v2, v2, v3, v5
	v_div_fixup_f32 v114, v2, v82, v161
	v_div_scale_f32 v2, s[0:1], v83, v83, v161
	v_rcp_f32_e32 v3, v2
	v_div_scale_f32 v4, vcc, v161, v83, v161
	v_fma_f32 v5, -v2, v3, 1.0
	v_fmac_f32_e32 v3, v5, v3
	v_mul_f32_e32 v5, v4, v3
	v_fma_f32 v6, -v2, v5, v4
	v_fmac_f32_e32 v5, v6, v3
	v_fma_f32 v2, -v2, v5, v4
	v_div_fmas_f32 v2, v2, v3, v5
	v_div_fixup_f32 v115, v2, v83, v161
	v_div_scale_f32 v2, s[0:1], v84, v84, v161
	v_rcp_f32_e32 v3, v2
	v_div_scale_f32 v4, vcc, v161, v84, v161
	v_fma_f32 v5, -v2, v3, 1.0
	v_fmac_f32_e32 v3, v5, v3
	v_mul_f32_e32 v5, v4, v3
	v_fma_f32 v6, -v2, v5, v4
	v_fmac_f32_e32 v5, v6, v3
	v_fma_f32 v2, -v2, v5, v4
	v_div_fmas_f32 v2, v2, v3, v5
	v_div_fixup_f32 v116, v2, v84, v161
	v_div_scale_f32 v2, s[0:1], v85, v85, v161
	v_rcp_f32_e32 v3, v2
	v_div_scale_f32 v4, vcc, v161, v85, v161
	v_fma_f32 v5, -v2, v3, 1.0
	v_fmac_f32_e32 v3, v5, v3
	v_mul_f32_e32 v5, v4, v3
	v_fma_f32 v6, -v2, v5, v4
	v_fmac_f32_e32 v5, v6, v3
	v_fma_f32 v2, -v2, v5, v4
	v_div_fmas_f32 v2, v2, v3, v5
	v_div_fixup_f32 v117, v2, v85, v161
	v_div_scale_f32 v2, s[0:1], v86, v86, v161
	v_rcp_f32_e32 v3, v2
	v_div_scale_f32 v4, vcc, v161, v86, v161
	v_fma_f32 v5, -v2, v3, 1.0
	v_fmac_f32_e32 v3, v5, v3
	v_mul_f32_e32 v5, v4, v3
	v_fma_f32 v6, -v2, v5, v4
	v_fmac_f32_e32 v5, v6, v3
	v_fma_f32 v2, -v2, v5, v4
	v_div_fmas_f32 v2, v2, v3, v5
	v_div_fixup_f32 v118, v2, v86, v161
	v_div_scale_f32 v2, s[0:1], v87, v87, v161
	v_rcp_f32_e32 v3, v2
	v_div_scale_f32 v4, vcc, v161, v87, v161
	v_fma_f32 v5, -v2, v3, 1.0
	v_fmac_f32_e32 v3, v5, v3
	v_mul_f32_e32 v5, v4, v3
	v_fma_f32 v6, -v2, v5, v4
	v_fmac_f32_e32 v5, v6, v3
	v_fma_f32 v2, -v2, v5, v4
	v_div_fmas_f32 v2, v2, v3, v5
	v_div_fixup_f32 v119, v2, v87, v161
	v_div_scale_f32 v2, s[0:1], v88, v88, v161
	v_rcp_f32_e32 v3, v2
	v_div_scale_f32 v4, vcc, v161, v88, v161
	v_fma_f32 v5, -v2, v3, 1.0
	v_fmac_f32_e32 v3, v5, v3
	v_mul_f32_e32 v5, v4, v3
	v_fma_f32 v6, -v2, v5, v4
	v_fmac_f32_e32 v5, v6, v3
	v_fma_f32 v2, -v2, v5, v4
	v_div_fmas_f32 v2, v2, v3, v5
	v_div_fixup_f32 v120, v2, v88, v161
	v_div_scale_f32 v2, s[0:1], v89, v89, v161
	v_rcp_f32_e32 v3, v2
	v_div_scale_f32 v4, vcc, v161, v89, v161
	v_fma_f32 v5, -v2, v3, 1.0
	v_fmac_f32_e32 v3, v5, v3
	v_mul_f32_e32 v5, v4, v3
	v_fma_f32 v6, -v2, v5, v4
	v_fmac_f32_e32 v5, v6, v3
	v_fma_f32 v2, -v2, v5, v4
	v_div_fmas_f32 v2, v2, v3, v5
	v_div_fixup_f32 v121, v2, v89, v161
	v_div_scale_f32 v2, s[0:1], v90, v90, v161
	v_rcp_f32_e32 v3, v2
	v_div_scale_f32 v4, vcc, v161, v90, v161
	v_fma_f32 v5, -v2, v3, 1.0
	v_fmac_f32_e32 v3, v5, v3
	v_mul_f32_e32 v5, v4, v3
	v_fma_f32 v6, -v2, v5, v4
	v_fmac_f32_e32 v5, v6, v3
	v_fma_f32 v2, -v2, v5, v4
	v_div_fmas_f32 v2, v2, v3, v5
	v_div_fixup_f32 v122, v2, v90, v161
	v_div_scale_f32 v2, s[0:1], v91, v91, v161
	v_rcp_f32_e32 v3, v2
	v_div_scale_f32 v4, vcc, v161, v91, v161
	v_fma_f32 v5, -v2, v3, 1.0
	v_fmac_f32_e32 v3, v5, v3
; __device__ __forceinline__ float bf_lo(unsigned u) { return __uint_as_float(u << 16); }
; __device__ __forceinline__ float bf_hi(unsigned u) { return __uint_as_float(u & 0xffff0000u); }
; __device__ __forceinline__ void diff_unit(const Params& p, LAS unsigned char* lds, int b, int h, int qb, float lam) {
;     ...
;         for (int r = 0; r < 16; ++r) { const float a = (mp == 0 ? 1.0f : lam) / L[r];
; #pragma unroll
;             for (int db = 0; db < 4; ++db) O[db][r] *= a; }
;     ...
;         for (int db = 0; db < 4; ++db) { const unsigned w = park[(db * 8 + (r >> 1)) * 64]; o[db] = ((r & 1) ? bf_hi(w) : bf_lo(w)) - O[db][r]; ss += o[db] * o[db]; }
	v_mul_f32_e32 v5, v4, v3
	v_fma_f32 v6, -v2, v5, v4
	v_fmac_f32_e32 v5, v6, v3
	v_fma_f32 v2, -v2, v5, v4
	v_div_fmas_f32 v2, v2, v3, v5
	v_div_fixup_f32 v123, v2, v91, v161
	v_div_scale_f32 v2, s[0:1], v92, v92, v161
	v_rcp_f32_e32 v3, v2
	v_div_scale_f32 v4, vcc, v161, v92, v161
	v_fma_f32 v5, -v2, v3, 1.0
	v_fmac_f32_e32 v3, v5, v3
	v_mul_f32_e32 v5, v4, v3
	v_fma_f32 v6, -v2, v5, v4
	v_fmac_f32_e32 v5, v6, v3
	v_fma_f32 v2, -v2, v5, v4
	v_div_fmas_f32 v2, v2, v3, v5
	v_div_fixup_f32 v124, v2, v92, v161
	v_div_scale_f32 v2, s[0:1], v93, v93, v161
	v_rcp_f32_e32 v3, v2
	v_div_scale_f32 v4, vcc, v161, v93, v161
	v_fma_f32 v5, -v2, v3, 1.0
	v_fmac_f32_e32 v3, v5, v3
	v_mul_f32_e32 v5, v4, v3
	v_fma_f32 v6, -v2, v5, v4
	v_fmac_f32_e32 v5, v6, v3
	v_fma_f32 v2, -v2, v5, v4
	v_div_fmas_f32 v2, v2, v3, v5
	v_div_fixup_f32 v125, v2, v93, v161
	v_div_scale_f32 v2, s[0:1], v94, v94, v161
	v_rcp_f32_e32 v3, v2
	v_div_scale_f32 v4, vcc, v161, v94, v161
	v_fma_f32 v5, -v2, v3, 1.0
	v_fmac_f32_e32 v3, v5, v3
	v_mul_f32_e32 v5, v4, v3
	v_fma_f32 v6, -v2, v5, v4
	v_fmac_f32_e32 v5, v6, v3
	v_fma_f32 v2, -v2, v5, v4
	v_div_fmas_f32 v2, v2, v3, v5
	v_div_fixup_f32 v126, v2, v94, v161
	v_div_scale_f32 v2, s[0:1], v95, v95, v161
	v_rcp_f32_e32 v3, v2
	v_div_scale_f32 v4, vcc, v161, v95, v161
	v_fma_f32 v5, -v2, v3, 1.0
	v_fmac_f32_e32 v3, v5, v3
	v_mul_f32_e32 v5, v4, v3
	v_fma_f32 v6, -v2, v5, v4
	v_fmac_f32_e32 v5, v6, v3
	v_fma_f32 v2, -v2, v5, v4
	v_div_fmas_f32 v2, v2, v3, v5
	v_div_fixup_f32 v127, v2, v95, v161
	s_waitcnt vmcnt(0)
	v_lshlrev_b32_e32 v128, 16, v136
	v_and_b32_e32 v129, 0xffff0000, v136
	v_pk_fma_f32 v[16:17], v[16:17], v[112:113], v[128:129] neg_lo:[1,0,0] neg_hi:[1,0,0]
	v_lshlrev_b32_e32 v130, 16, v137
	v_and_b32_e32 v131, 0xffff0000, v137
	v_pk_fma_f32 v[18:19], v[18:19], v[114:115], v[130:131] neg_lo:[1,0,0] neg_hi:[1,0,0]
	v_lshlrev_b32_e32 v128, 16, v138
	v_and_b32_e32 v129, 0xffff0000, v138
	v_pk_fma_f32 v[20:21], v[20:21], v[116:117], v[128:129] neg_lo:[1,0,0] neg_hi:[1,0,0]
	v_lshlrev_b32_e32 v130, 16, v139
	v_and_b32_e32 v131, 0xffff0000, v139
	v_pk_fma_f32 v[22:23], v[22:23], v[118:119], v[130:131] neg_lo:[1,0,0] neg_hi:[1,0,0]
	v_lshlrev_b32_e32 v128, 16, v140
	v_and_b32_e32 v129, 0xffff0000, v140
	v_pk_fma_f32 v[24:25], v[24:25], v[120:121], v[128:129] neg_lo:[1,0,0] neg_hi:[1,0,0]
	v_lshlrev_b32_e32 v130, 16, v141
	v_and_b32_e32 v131, 0xffff0000, v141
	v_pk_fma_f32 v[26:27], v[26:27], v[122:123], v[130:131] neg_lo:[1,0,0] neg_hi:[1,0,0]
	v_lshlrev_b32_e32 v128, 16, v142
	v_and_b32_e32 v129, 0xffff0000, v142
	v_pk_fma_f32 v[28:29], v[28:29], v[124:125], v[128:129] neg_lo:[1,0,0] neg_hi:[1,0,0]
	v_lshlrev_b32_e32 v130, 16, v143
	v_and_b32_e32 v131, 0xffff0000, v143
	v_pk_fma_f32 v[30:31], v[30:31], v[126:127], v[130:131] neg_lo:[1,0,0] neg_hi:[1,0,0]
	v_lshlrev_b32_e32 v128, 16, v144
	v_and_b32_e32 v129, 0xffff0000, v144
	v_pk_fma_f32 v[32:33], v[32:33], v[112:113], v[128:129] neg_lo:[1,0,0] neg_hi:[1,0,0]
	v_lshlrev_b32_e32 v130, 16, v145
	v_and_b32_e32 v131, 0xffff0000, v145
	v_pk_fma_f32 v[34:35], v[34:35], v[114:115], v[130:131] neg_lo:[1,0,0] neg_hi:[1,0,0]
	v_lshlrev_b32_e32 v128, 16, v146
	v_and_b32_e32 v129, 0xffff0000, v146
	v_pk_fma_f32 v[36:37], v[36:37], v[116:117], v[128:129] neg_lo:[1,0,0] neg_hi:[1,0,0]
	v_lshlrev_b32_e32 v130, 16, v147
	v_and_b32_e32 v131, 0xffff0000, v147
	v_pk_fma_f32 v[38:39], v[38:39], v[118:119], v[130:131] neg_lo:[1,0,0] neg_hi:[1,0,0]
	v_lshlrev_b32_e32 v128, 16, v148
	v_and_b32_e32 v129, 0xffff0000, v148
	v_pk_fma_f32 v[40:41], v[40:41], v[120:121], v[128:129] neg_lo:[1,0,0] neg_hi:[1,0,0]
	v_lshlrev_b32_e32 v130, 16, v149
	v_and_b32_e32 v131, 0xffff0000, v149
	v_pk_fma_f32 v[42:43], v[42:43], v[122:123], v[130:131] neg_lo:[1,0,0] neg_hi:[1,0,0]
	v_lshlrev_b32_e32 v128, 16, v150
	v_and_b32_e32 v129, 0xffff0000, v150
	v_pk_fma_f32 v[44:45], v[44:45], v[124:125], v[128:129] neg_lo:[1,0,0] neg_hi:[1,0,0]
	v_lshlrev_b32_e32 v130, 16, v151
	v_and_b32_e32 v131, 0xffff0000, v151
	v_pk_fma_f32 v[46:47], v[46:47], v[126:127], v[130:131] neg_lo:[1,0,0] neg_hi:[1,0,0]
	v_lshlrev_b32_e32 v128, 16, v152
	v_and_b32_e32 v129, 0xffff0000, v152
	v_pk_fma_f32 v[48:49], v[48:49], v[112:113], v[128:129] neg_lo:[1,0,0] neg_hi:[1,0,0]
	v_lshlrev_b32_e32 v130, 16, v153
	v_and_b32_e32 v131, 0xffff0000, v153
	v_pk_fma_f32 v[50:51], v[50:51], v[114:115], v[130:131] neg_lo:[1,0,0] neg_hi:[1,0,0]
	v_lshlrev_b32_e32 v128, 16, v154
	v_and_b32_e32 v129, 0xffff0000, v154
	v_pk_fma_f32 v[52:53], v[52:53], v[116:117], v[128:129] neg_lo:[1,0,0] neg_hi:[1,0,0]
	v_lshlrev_b32_e32 v130, 16, v155
	v_and_b32_e32 v131, 0xffff0000, v155
	v_pk_fma_f32 v[54:55], v[54:55], v[118:119], v[130:131] neg_lo:[1,0,0] neg_hi:[1,0,0]
	v_lshlrev_b32_e32 v128, 16, v156
	v_and_b32_e32 v129, 0xffff0000, v156
	v_pk_fma_f32 v[56:57], v[56:57], v[120:121], v[128:129] neg_lo:[1,0,0] neg_hi:[1,0,0]
	v_lshlrev_b32_e32 v130, 16, v157
	v_and_b32_e32 v131, 0xffff0000, v157
	v_pk_fma_f32 v[58:59], v[58:59], v[122:123], v[130:131] neg_lo:[1,0,0] neg_hi:[1,0,0]
	v_lshlrev_b32_e32 v128, 16, v158
	v_and_b32_e32 v129, 0xffff0000, v158
	v_pk_fma_f32 v[60:61], v[60:61], v[124:125], v[128:129] neg_lo:[1,0,0] neg_hi:[1,0,0]
	v_lshlrev_b32_e32 v130, 16, v159
	v_and_b32_e32 v131, 0xffff0000, v159
	v_pk_fma_f32 v[62:63], v[62:63], v[126:127], v[130:131] neg_lo:[1,0,0] neg_hi:[1,0,0]
	v_lshlrev_b32_e32 v128, 16, v176
	v_and_b32_e32 v129, 0xffff0000, v176
	v_pk_fma_f32 v[64:65], v[64:65], v[112:113], v[128:129] neg_lo:[1,0,0] neg_hi:[1,0,0]
	v_lshlrev_b32_e32 v130, 16, v177
	v_and_b32_e32 v131, 0xffff0000, v177
	v_pk_fma_f32 v[66:67], v[66:67], v[114:115], v[130:131] neg_lo:[1,0,0] neg_hi:[1,0,0]
; __device__ __forceinline__ float bf_lo(unsigned u) { return __uint_as_float(u << 16); }
; __device__ __forceinline__ float bf_hi(unsigned u) { return __uint_as_float(u & 0xffff0000u); }
; __device__ __forceinline__ int crow(int r, int h) { return (r & 3) + 8 * (r >> 2) + 4 * h; }
; __device__ __forceinline__ void diff_unit(const Params& p, LAS unsigned char* lds, int b, int h, int qb, float lam) {
;     ...
;     for (int db = 0; db < 4; ++db) gn[db] = p.diff_gain[32 * db + c] * 0.8f;
; #pragma unroll
;     for (int r = 0; r < 16; ++r) {
;         const int qr = crow(r, hh);
;         float o[4]; float ss = 0.f;
; #pragma unroll
;         for (int db = 0; db < 4; ++db) { const unsigned w = park[(db * 8 + (r >> 1)) * 64]; o[db] = ((r & 1) ? bf_hi(w) : bf_lo(w)) - O[db][r]; ss += o[db] * o[db]; }
; #pragma unroll
;         for (int off = 1; off < 32; off <<= 1) ss += __shfl_xor(ss, off);
	v_lshlrev_b32_e32 v128, 16, v178
	v_and_b32_e32 v129, 0xffff0000, v178
	v_pk_fma_f32 v[68:69], v[68:69], v[116:117], v[128:129] neg_lo:[1,0,0] neg_hi:[1,0,0]
	v_lshlrev_b32_e32 v130, 16, v179
	v_and_b32_e32 v131, 0xffff0000, v179
	v_pk_fma_f32 v[70:71], v[70:71], v[118:119], v[130:131] neg_lo:[1,0,0] neg_hi:[1,0,0]
	v_lshlrev_b32_e32 v128, 16, v180
	v_and_b32_e32 v129, 0xffff0000, v180
	v_pk_fma_f32 v[72:73], v[72:73], v[120:121], v[128:129] neg_lo:[1,0,0] neg_hi:[1,0,0]
	v_lshlrev_b32_e32 v130, 16, v181
	v_and_b32_e32 v131, 0xffff0000, v181
	v_pk_fma_f32 v[74:75], v[74:75], v[122:123], v[130:131] neg_lo:[1,0,0] neg_hi:[1,0,0]
	v_lshlrev_b32_e32 v128, 16, v182
	v_and_b32_e32 v129, 0xffff0000, v182
	v_pk_fma_f32 v[76:77], v[76:77], v[124:125], v[128:129] neg_lo:[1,0,0] neg_hi:[1,0,0]
	v_lshlrev_b32_e32 v130, 16, v183
	v_and_b32_e32 v131, 0xffff0000, v183
	v_pk_fma_f32 v[78:79], v[78:79], v[126:127], v[130:131] neg_lo:[1,0,0] neg_hi:[1,0,0]
	v_and_b32_e32 v12, 31, v163
	v_lshrrev_b32_e32 v13, 5, v163
	v_xor_b32_e32 v171, 16, v163
	v_xor_b32_e32 v170, 8, v163
	v_xor_b32_e32 v169, 4, v163
	v_xor_b32_e32 v168, 2, v163
	v_xor_b32_e32 v147, 1, v163
	v_lshlrev_b32_e32 v171, 2, v171
	v_lshlrev_b32_e32 v170, 2, v170
	v_lshlrev_b32_e32 v169, 2, v169
	v_lshlrev_b32_e32 v168, 2, v168
	v_lshlrev_b32_e32 v147, 2, v147
	v_and_b32_e32 v11, 16, v163
	v_cmp_ne_u32_e64 s[0:1], 0, v11
	v_and_b32_e32 v11, 8, v163
	v_cmp_ne_u32_e64 s[4:5], 0, v11
	v_and_b32_e32 v11, 4, v163
	v_cmp_ne_u32_e64 s[98:99], 0, v11
	v_and_b32_e32 v11, 2, v163
	v_cmp_ne_u32_e64 s[100:101], 0, v11
	v_lshlrev_b32_e32 v14, 2, v12
	global_load_dword v220, v14, s[54:55] offset:0
	global_load_dword v222, v14, s[54:55] offset:128
	global_load_dword v224, v14, s[54:55] offset:256
	global_load_dword v226, v14, s[54:55] offset:384
	v_mov_b32_e32 v7, 0x358637bd
	v_mov_b32_e32 v8, 0x260
	v_pk_mul_f32 v[96:97], v[16:17], v[16:17]
	v_pk_fma_f32 v[96:97], v[32:33], v[32:33], v[96:97]
	v_pk_fma_f32 v[96:97], v[48:49], v[48:49], v[96:97]
	v_pk_fma_f32 v[96:97], v[64:65], v[64:65], v[96:97]
	v_pk_mul_f32 v[98:99], v[18:19], v[18:19]
	v_pk_fma_f32 v[98:99], v[34:35], v[34:35], v[98:99]
	v_pk_fma_f32 v[98:99], v[50:51], v[50:51], v[98:99]
	v_pk_fma_f32 v[98:99], v[66:67], v[66:67], v[98:99]
	v_pk_mul_f32 v[100:101], v[20:21], v[20:21]
	v_pk_fma_f32 v[100:101], v[36:37], v[36:37], v[100:101]
	v_pk_fma_f32 v[100:101], v[52:53], v[52:53], v[100:101]
	v_pk_fma_f32 v[100:101], v[68:69], v[68:69], v[100:101]
	v_pk_mul_f32 v[102:103], v[22:23], v[22:23]
	v_pk_fma_f32 v[102:103], v[38:39], v[38:39], v[102:103]
	v_pk_fma_f32 v[102:103], v[54:55], v[54:55], v[102:103]
	v_pk_fma_f32 v[102:103], v[70:71], v[70:71], v[102:103]
	v_pk_mul_f32 v[104:105], v[24:25], v[24:25]
	v_pk_fma_f32 v[104:105], v[40:41], v[40:41], v[104:105]
	v_pk_fma_f32 v[104:105], v[56:57], v[56:57], v[104:105]
	v_pk_fma_f32 v[104:105], v[72:73], v[72:73], v[104:105]
	v_pk_mul_f32 v[106:107], v[26:27], v[26:27]
	v_pk_fma_f32 v[106:107], v[42:43], v[42:43], v[106:107]
	v_pk_fma_f32 v[106:107], v[58:59], v[58:59], v[106:107]
	v_pk_fma_f32 v[106:107], v[74:75], v[74:75], v[106:107]
	v_pk_mul_f32 v[108:109], v[28:29], v[28:29]
	v_pk_fma_f32 v[108:109], v[44:45], v[44:45], v[108:109]
	v_pk_fma_f32 v[108:109], v[60:61], v[60:61], v[108:109]
	v_pk_fma_f32 v[108:109], v[76:77], v[76:77], v[108:109]
	v_pk_mul_f32 v[110:111], v[30:31], v[30:31]
	v_pk_fma_f32 v[110:111], v[46:47], v[46:47], v[110:111]
	v_pk_fma_f32 v[110:111], v[62:63], v[62:63], v[110:111]
	v_pk_fma_f32 v[110:111], v[78:79], v[78:79], v[110:111]
	v_cndmask_b32_e64 v112, v96, v104, s[0:1]
	v_cndmask_b32_e64 v120, v104, v96, s[0:1]
	v_cndmask_b32_e64 v113, v97, v105, s[0:1]
	v_cndmask_b32_e64 v121, v105, v97, s[0:1]
	v_cndmask_b32_e64 v114, v98, v106, s[0:1]
	v_cndmask_b32_e64 v122, v106, v98, s[0:1]
	v_cndmask_b32_e64 v115, v99, v107, s[0:1]
	v_cndmask_b32_e64 v123, v107, v99, s[0:1]
	v_cndmask_b32_e64 v116, v100, v108, s[0:1]
	v_cndmask_b32_e64 v124, v108, v100, s[0:1]
	v_cndmask_b32_e64 v117, v101, v109, s[0:1]
	v_cndmask_b32_e64 v125, v109, v101, s[0:1]
	v_cndmask_b32_e64 v118, v102, v110, s[0:1]
	v_cndmask_b32_e64 v126, v110, v102, s[0:1]
	v_cndmask_b32_e64 v119, v103, v111, s[0:1]
	v_cndmask_b32_e64 v127, v111, v103, s[0:1]
	ds_bpermute_b32 v128, v171, v120
	ds_bpermute_b32 v129, v171, v121
	ds_bpermute_b32 v130, v171, v122
	ds_bpermute_b32 v131, v171, v123
	ds_bpermute_b32 v132, v171, v124
	ds_bpermute_b32 v133, v171, v125
	ds_bpermute_b32 v134, v171, v126
	ds_bpermute_b32 v135, v171, v127
	s_waitcnt lgkmcnt(0)
	v_add_f32_e32 v112, v112, v128
	v_add_f32_e32 v113, v113, v129
	v_add_f32_e32 v114, v114, v130
	v_add_f32_e32 v115, v115, v131
	v_add_f32_e32 v116, v116, v132
	v_add_f32_e32 v117, v117, v133
	v_add_f32_e32 v118, v118, v134
	v_add_f32_e32 v119, v119, v135
	v_cndmask_b32_e64 v136, v112, v116, s[4:5]
	v_cndmask_b32_e64 v140, v116, v112, s[4:5]
	v_cndmask_b32_e64 v137, v113, v117, s[4:5]
	v_cndmask_b32_e64 v141, v117, v113, s[4:5]
	v_cndmask_b32_e64 v138, v114, v118, s[4:5]
	v_cndmask_b32_e64 v142, v118, v114, s[4:5]
	v_cndmask_b32_e64 v139, v115, v119, s[4:5]
	v_cndmask_b32_e64 v143, v119, v115, s[4:5]
	ds_bpermute_b32 v148, v170, v140
	ds_bpermute_b32 v149, v170, v141
	ds_bpermute_b32 v150, v170, v142
	ds_bpermute_b32 v151, v170, v143
	s_waitcnt lgkmcnt(0)
	v_add_f32_e32 v136, v136, v148
	v_add_f32_e32 v137, v137, v149
	v_add_f32_e32 v138, v138, v150
	v_add_f32_e32 v139, v139, v151
	v_cndmask_b32_e64 v152, v136, v138, s[98:99]
	v_cndmask_b32_e64 v154, v138, v136, s[98:99]
	v_cndmask_b32_e64 v153, v137, v139, s[98:99]
	v_cndmask_b32_e64 v155, v139, v137, s[98:99]
	ds_bpermute_b32 v156, v169, v154
	ds_bpermute_b32 v157, v169, v155
	s_waitcnt lgkmcnt(0)
; __device__ __forceinline__ unsigned cvtpk(float lo, float hi) { f32x2_t v = {lo, hi}; bf16x2_t b = __builtin_convertvector(v, bf16x2_t); return __builtin_bit_cast(unsigned, b); }
; __device__ __forceinline__ void diff_unit(const Params& p, LAS unsigned char* lds, int b, int h, int qb, float lam) {
;     ...
; #pragma unroll
;         for (int off = 1; off < 32; off <<= 1) ss += __shfl_xor(ss, off);
;         const float rs = 1.0f / sqrtf(ss * (1.0f / 128.0f) + EPS);
;         bf16_t* op = AO + (rowbase + q0 + qr) * DM + h * 128 + c;
; #pragma unroll
;         for (int db = 0; db < 4; ++db) op[32 * db] = (bf16_t)(cvtpk(o[db] * rs * gn[db], 0.f) & 0xffffu);
	v_add_f32_e32 v152, v152, v156
	v_add_f32_e32 v153, v153, v157
	v_cndmask_b32_e64 v158, v152, v153, s[100:101]
	v_cndmask_b32_e64 v159, v153, v152, s[100:101]
	ds_bpermute_b32 v166, v168, v159
	s_waitcnt lgkmcnt(0)
	v_add_f32_e32 v158, v158, v166
	ds_bpermute_b32 v166, v147, v158
	s_waitcnt lgkmcnt(0)
	v_add_f32_e32 v158, v158, v166
	v_fmamk_f32 v158, v158, 0x3c000000, v7
	v_mul_f32_e32 v2, 0x4f800000, v158
	v_cmp_gt_f32_e32 vcc, 0xf800000, v158
	s_nop 1
	v_cndmask_b32_e32 v158, v158, v2, vcc
	v_sqrt_f32_e32 v2, v158
	s_nop 0
	v_add_u32_e32 v3, -1, v2
	v_add_u32_e32 v4, 1, v2
	v_fma_f32 v5, -v3, v2, v158
	v_fma_f32 v6, -v4, v2, v158
	v_cmp_ge_f32_e64 s[0:1], 0, v5
	s_nop 1
	v_cndmask_b32_e64 v2, v2, v3, s[0:1]
	v_cmp_lt_f32_e64 s[0:1], 0, v6
	s_nop 1
	v_cndmask_b32_e64 v2, v2, v4, s[0:1]
	v_mul_f32_e32 v3, 0x37800000, v2
	v_cndmask_b32_e32 v2, v2, v3, vcc
	v_cmp_class_f32_e32 vcc, v158, v8
	s_nop 1
	v_cndmask_b32_e32 v158, v2, v158, vcc
	v_div_scale_f32 v2, s[0:1], v158, v158, 1.0
	v_rcp_f32_e32 v4, v2
	v_div_scale_f32 v3, vcc, 1.0, v158, 1.0
	v_fma_f32 v5, -v2, v4, 1.0
	v_fmac_f32_e32 v4, v5, v4
	v_mul_f32_e32 v5, v3, v4
	v_fma_f32 v6, -v2, v5, v3
	v_fmac_f32_e32 v5, v6, v4
	v_fma_f32 v2, -v2, v5, v3
	v_div_fmas_f32 v2, v2, v4, v5
	v_div_fixup_f32 v159, v2, v158, 1.0
	v_readfirstlane_b32 s1, v162
	s_nop 3
	s_lshr_b32 s1, s1, 6
	s_lshl_b32 s1, s1, 7
	s_add_u32 s1, s1, 0x10800
	v_and_b32_e32 v11, 30, v12
	v_lshlrev_b32_e32 v11, 1, v11
	v_lshl_add_u32 v11, v13, 6, v11
	v_add_u32_e32 v9, s1, v11
	v_lshlrev_b32_e32 v10, 6, v13
	v_add_u32_e32 v10, s1, v10
	ds_write_b32 v9, v159
	s_waitcnt lgkmcnt(0)
	ds_read_b128 v[176:179], v10
	ds_read_b128 v[180:183], v10 offset:16
	ds_read_b128 v[184:187], v10 offset:32
	ds_read_b128 v[216:219], v10 offset:48
	s_and_b32 s0, s72, 3
	s_lshr_b32 s1, s72, 8
	s_xor_b32 s4, s0, 7
	s_or_b32 s5, s0, 8
	s_xor_b32 s98, s0, 15
	s_cmp_eq_u32 s1, 1
	s_cselect_b32 s0, s4, s0
	s_cmp_eq_u32 s1, 2
	s_cselect_b32 s0, s5, s0
	s_cmp_eq_u32 s1, 3
	s_cselect_b32 s0, s98, s0
	v_readfirstlane_b32 s1, v162
	s_nop 3
	s_lshr_b32 s1, s1, 6
	s_lshl_b32 s0, s0, 8
	s_lshl_b32 s1, s1, 5
	s_add_u32 s0, s0, s1
	s_bfe_u32 s1, s72, 0x30005
	s_lshl_b32 s1, s1, 12
	s_add_u32 s0, s0, s1
	s_lshl_b32 s4, s0, 12
	s_bfe_u32 s1, s72, 0x30002
	s_lshl_b32 s1, s1, 8
	s_add_u32 s4, s4, s1
	s_add_u32 s0, s28, 0x2e000000
	s_addc_u32 s1, s29, 0
	s_add_u32 s0, s0, s4
	s_addc_u32 s1, s1, 0
	s_add_u32 s4, s0, 0x10000
	s_addc_u32 s5, s1, 0
	v_readfirstlane_b32 s98, v162
	s_nop 3
	s_lshr_b32 s98, s98, 6
	s_lshl_b32 s98, s98, 12
	s_add_u32 s98, s98, 0x11000
	v_lshlrev_b32_e32 v11, 9, v13
	v_lshl_add_u32 v11, v12, 1, v11
	v_add_u32_e32 v228, s98, v11
	v_lshlrev_b32_e32 v11, 4, v163
	v_add_u32_e32 v229, s98, v11
	v_lshrrev_b32_e32 v11, 3, v163
	v_lshlrev_b32_e32 v11, 12, v11
	v_and_b32_e32 v230, 7, v163
	v_lshl_add_u32 v230, v230, 4, v11
	v_add_u32_e32 v231, 0x8000, v230
	s_waitcnt vmcnt(0) lgkmcnt(0)
	v_mul_f32_e32 v220, 0x3f4ccccd, v220
	v_mul_f32_e32 v222, 0x3f4ccccd, v222
	v_mul_f32_e32 v224, 0x3f4ccccd, v224
	v_mul_f32_e32 v226, 0x3f4ccccd, v226
	v_pk_mul_f32 v[236:237], v[16:17], v[176:177]
	v_pk_mul_f32 v[236:237], v[236:237], v[220:221] op_sel_hi:[1,0]
	v_cvt_pk_bf16_f32 v240, v236, v237
	ds_write_b16 v228, v240
	ds_write_b16_d16_hi v228, v240 offset:128
	v_pk_mul_f32 v[238:239], v[18:19], v[178:179]
	v_pk_mul_f32 v[238:239], v[238:239], v[220:221] op_sel_hi:[1,0]
	v_cvt_pk_bf16_f32 v241, v238, v239
	ds_write_b16 v228, v241 offset:256
	ds_write_b16_d16_hi v228, v241 offset:384
	v_pk_mul_f32 v[236:237], v[20:21], v[180:181]
	v_pk_mul_f32 v[236:237], v[236:237], v[220:221] op_sel_hi:[1,0]
	v_cvt_pk_bf16_f32 v242, v236, v237
	ds_write_b16 v228, v242 offset:1024
	ds_write_b16_d16_hi v228, v242 offset:1152
	v_pk_mul_f32 v[238:239], v[22:23], v[182:183]
	v_pk_mul_f32 v[238:239], v[238:239], v[220:221] op_sel_hi:[1,0]
	v_cvt_pk_bf16_f32 v243, v238, v239
	ds_write_b16 v228, v243 offset:1280
	ds_write_b16_d16_hi v228, v243 offset:1408
	v_pk_mul_f32 v[236:237], v[24:25], v[184:185]
	v_pk_mul_f32 v[236:237], v[236:237], v[220:221] op_sel_hi:[1,0]
	v_cvt_pk_bf16_f32 v244, v236, v237
	ds_write_b16 v228, v244 offset:2048
	ds_write_b16_d16_hi v228, v244 offset:2176
	v_pk_mul_f32 v[238:239], v[26:27], v[186:187]
	v_pk_mul_f32 v[238:239], v[238:239], v[220:221] op_sel_hi:[1,0]
	v_cvt_pk_bf16_f32 v213, v238, v239
	ds_write_b16 v228, v213 offset:2304
	ds_write_b16_d16_hi v228, v213 offset:2432
	v_pk_mul_f32 v[236:237], v[28:29], v[216:217]
	v_pk_mul_f32 v[236:237], v[236:237], v[220:221] op_sel_hi:[1,0]
	v_cvt_pk_bf16_f32 v214, v236, v237
	ds_write_b16 v228, v214 offset:3072
	ds_write_b16_d16_hi v228, v214 offset:3200
	v_pk_mul_f32 v[238:239], v[30:31], v[218:219]
	v_pk_mul_f32 v[238:239], v[238:239], v[220:221] op_sel_hi:[1,0]
	v_cvt_pk_bf16_f32 v215, v238, v239
	ds_write_b16 v228, v215 offset:3328
	ds_write_b16_d16_hi v228, v215 offset:3456
	v_pk_mul_f32 v[236:237], v[32:33], v[176:177]
	v_pk_mul_f32 v[236:237], v[236:237], v[222:223] op_sel_hi:[1,0]
	v_cvt_pk_bf16_f32 v240, v236, v237
	ds_write_b16 v228, v240 offset:64
	ds_write_b16_d16_hi v228, v240 offset:192
	v_pk_mul_f32 v[238:239], v[34:35], v[178:179]
	v_pk_mul_f32 v[238:239], v[238:239], v[222:223] op_sel_hi:[1,0]
	v_cvt_pk_bf16_f32 v241, v238, v239
	ds_write_b16 v228, v241 offset:320
	ds_write_b16_d16_hi v228, v241 offset:448
	v_pk_mul_f32 v[236:237], v[36:37], v[180:181]
	v_pk_mul_f32 v[236:237], v[236:237], v[222:223] op_sel_hi:[1,0]
	v_cvt_pk_bf16_f32 v242, v236, v237
	ds_write_b16 v228, v242 offset:1088
	ds_write_b16_d16_hi v228, v242 offset:1216
	v_pk_mul_f32 v[238:239], v[38:39], v[182:183]
	v_pk_mul_f32 v[238:239], v[238:239], v[222:223] op_sel_hi:[1,0]
	v_cvt_pk_bf16_f32 v243, v238, v239
	ds_write_b16 v228, v243 offset:1344
	ds_write_b16_d16_hi v228, v243 offset:1472
	v_pk_mul_f32 v[236:237], v[40:41], v[184:185]
	v_pk_mul_f32 v[236:237], v[236:237], v[222:223] op_sel_hi:[1,0]
	v_cvt_pk_bf16_f32 v244, v236, v237
	ds_write_b16 v228, v244 offset:2112
	ds_write_b16_d16_hi v228, v244 offset:2240
	v_pk_mul_f32 v[238:239], v[42:43], v[186:187]
	v_pk_mul_f32 v[238:239], v[238:239], v[222:223] op_sel_hi:[1,0]
	v_cvt_pk_bf16_f32 v213, v238, v239
	ds_write_b16 v228, v213 offset:2368
	ds_write_b16_d16_hi v228, v213 offset:2496
	v_pk_mul_f32 v[236:237], v[44:45], v[216:217]
	v_pk_mul_f32 v[236:237], v[236:237], v[222:223] op_sel_hi:[1,0]
	v_cvt_pk_bf16_f32 v214, v236, v237
	ds_write_b16 v228, v214 offset:3136
	ds_write_b16_d16_hi v228, v214 offset:3264
	v_pk_mul_f32 v[238:239], v[46:47], v[218:219]
	v_pk_mul_f32 v[238:239], v[238:239], v[222:223] op_sel_hi:[1,0]
	v_cvt_pk_bf16_f32 v215, v238, v239
	ds_write_b16 v228, v215 offset:3392
	ds_write_b16_d16_hi v228, v215 offset:3520
	ds_read_b128 v[16:19], v229
	ds_read_b128 v[20:23], v229 offset:1024
	ds_read_b128 v[24:27], v229 offset:2048
	ds_read_b128 v[28:31], v229 offset:3072
	s_waitcnt lgkmcnt(3)
; __device__ __forceinline__ unsigned cvtpk(float lo, float hi) { f32x2_t v = {lo, hi}; bf16x2_t b = __builtin_convertvector(v, bf16x2_t); return __builtin_bit_cast(unsigned, b); }
; __device__ __forceinline__ void diff_unit(const Params& p, LAS unsigned char* lds, int b, int h, int qb, float lam) {
;     ...
;         bf16_t* op = AO + (rowbase + q0 + qr) * DM + h * 128 + c;
; #pragma unroll
;         for (int db = 0; db < 4; ++db) op[32 * db] = (bf16_t)(cvtpk(o[db] * rs * gn[db], 0.f) & 0xffffu);
; __device__ __forceinline__ void attention_phase(const Params& p, LAS unsigned char* lds, int G, int blk) {
;     ...
;     for (int u = v; u < 1024; u += G) {
	global_store_dwordx4 v230, v[16:19], s[0:1]
	s_waitcnt lgkmcnt(2)
	global_store_dwordx4 v231, v[20:23], s[0:1]
	s_waitcnt lgkmcnt(1)
	global_store_dwordx4 v230, v[24:27], s[4:5]
	s_waitcnt lgkmcnt(0)
	global_store_dwordx4 v231, v[28:31], s[4:5]
	v_pk_mul_f32 v[236:237], v[48:49], v[176:177]
	v_pk_mul_f32 v[236:237], v[236:237], v[224:225] op_sel_hi:[1,0]
	v_cvt_pk_bf16_f32 v240, v236, v237
	ds_write_b16 v228, v240
	ds_write_b16_d16_hi v228, v240 offset:128
	v_pk_mul_f32 v[238:239], v[50:51], v[178:179]
	v_pk_mul_f32 v[238:239], v[238:239], v[224:225] op_sel_hi:[1,0]
	v_cvt_pk_bf16_f32 v241, v238, v239
	ds_write_b16 v228, v241 offset:256
	ds_write_b16_d16_hi v228, v241 offset:384
	v_pk_mul_f32 v[236:237], v[52:53], v[180:181]
	v_pk_mul_f32 v[236:237], v[236:237], v[224:225] op_sel_hi:[1,0]
	v_cvt_pk_bf16_f32 v242, v236, v237
	ds_write_b16 v228, v242 offset:1024
	ds_write_b16_d16_hi v228, v242 offset:1152
	v_pk_mul_f32 v[238:239], v[54:55], v[182:183]
	v_pk_mul_f32 v[238:239], v[238:239], v[224:225] op_sel_hi:[1,0]
	v_cvt_pk_bf16_f32 v243, v238, v239
	ds_write_b16 v228, v243 offset:1280
	ds_write_b16_d16_hi v228, v243 offset:1408
	v_pk_mul_f32 v[236:237], v[56:57], v[184:185]
	v_pk_mul_f32 v[236:237], v[236:237], v[224:225] op_sel_hi:[1,0]
	v_cvt_pk_bf16_f32 v244, v236, v237
	ds_write_b16 v228, v244 offset:2048
	ds_write_b16_d16_hi v228, v244 offset:2176
	v_pk_mul_f32 v[238:239], v[58:59], v[186:187]
	v_pk_mul_f32 v[238:239], v[238:239], v[224:225] op_sel_hi:[1,0]
	v_cvt_pk_bf16_f32 v213, v238, v239
	ds_write_b16 v228, v213 offset:2304
	ds_write_b16_d16_hi v228, v213 offset:2432
	v_pk_mul_f32 v[236:237], v[60:61], v[216:217]
	v_pk_mul_f32 v[236:237], v[236:237], v[224:225] op_sel_hi:[1,0]
	v_cvt_pk_bf16_f32 v214, v236, v237
	ds_write_b16 v228, v214 offset:3072
	ds_write_b16_d16_hi v228, v214 offset:3200
	v_pk_mul_f32 v[238:239], v[62:63], v[218:219]
	v_pk_mul_f32 v[238:239], v[238:239], v[224:225] op_sel_hi:[1,0]
	v_cvt_pk_bf16_f32 v215, v238, v239
	ds_write_b16 v228, v215 offset:3328
	ds_write_b16_d16_hi v228, v215 offset:3456
	v_pk_mul_f32 v[236:237], v[64:65], v[176:177]
	v_pk_mul_f32 v[236:237], v[236:237], v[226:227] op_sel_hi:[1,0]
	v_cvt_pk_bf16_f32 v240, v236, v237
	ds_write_b16 v228, v240 offset:64
	ds_write_b16_d16_hi v228, v240 offset:192
	v_pk_mul_f32 v[238:239], v[66:67], v[178:179]
	v_pk_mul_f32 v[238:239], v[238:239], v[226:227] op_sel_hi:[1,0]
	v_cvt_pk_bf16_f32 v241, v238, v239
	ds_write_b16 v228, v241 offset:320
	ds_write_b16_d16_hi v228, v241 offset:448
	v_pk_mul_f32 v[236:237], v[68:69], v[180:181]
	v_pk_mul_f32 v[236:237], v[236:237], v[226:227] op_sel_hi:[1,0]
	v_cvt_pk_bf16_f32 v242, v236, v237
	ds_write_b16 v228, v242 offset:1088
	ds_write_b16_d16_hi v228, v242 offset:1216
	v_pk_mul_f32 v[238:239], v[70:71], v[182:183]
	v_pk_mul_f32 v[238:239], v[238:239], v[226:227] op_sel_hi:[1,0]
	v_cvt_pk_bf16_f32 v243, v238, v239
	ds_write_b16 v228, v243 offset:1344
	ds_write_b16_d16_hi v228, v243 offset:1472
	v_pk_mul_f32 v[236:237], v[72:73], v[184:185]
	v_pk_mul_f32 v[236:237], v[236:237], v[226:227] op_sel_hi:[1,0]
	v_cvt_pk_bf16_f32 v244, v236, v237
	ds_write_b16 v228, v244 offset:2112
	ds_write_b16_d16_hi v228, v244 offset:2240
	v_pk_mul_f32 v[238:239], v[74:75], v[186:187]
	v_pk_mul_f32 v[238:239], v[238:239], v[226:227] op_sel_hi:[1,0]
	v_cvt_pk_bf16_f32 v213, v238, v239
	ds_write_b16 v228, v213 offset:2368
	ds_write_b16_d16_hi v228, v213 offset:2496
	v_pk_mul_f32 v[236:237], v[76:77], v[216:217]
	v_pk_mul_f32 v[236:237], v[236:237], v[226:227] op_sel_hi:[1,0]
	v_cvt_pk_bf16_f32 v214, v236, v237
	ds_write_b16 v228, v214 offset:3136
	ds_write_b16_d16_hi v228, v214 offset:3264
	v_pk_mul_f32 v[238:239], v[78:79], v[218:219]
	v_pk_mul_f32 v[238:239], v[238:239], v[226:227] op_sel_hi:[1,0]
	v_cvt_pk_bf16_f32 v215, v238, v239
	ds_write_b16 v228, v215 offset:3392
	ds_write_b16_d16_hi v228, v215 offset:3520
	ds_read_b128 v[48:51], v229
	ds_read_b128 v[52:55], v229 offset:1024
	ds_read_b128 v[56:59], v229 offset:2048
	ds_read_b128 v[60:63], v229 offset:3072
	s_waitcnt lgkmcnt(3)
	global_store_dwordx4 v230, v[48:51], s[0:1] offset:128
	s_waitcnt lgkmcnt(2)
	global_store_dwordx4 v231, v[52:55], s[0:1] offset:128
	s_waitcnt lgkmcnt(1)
	global_store_dwordx4 v230, v[56:59], s[4:5] offset:128
	s_waitcnt lgkmcnt(0)
	global_store_dwordx4 v231, v[60:63], s[4:5] offset:128
	v_add_u32_e32 v80, 64, v194
	s_add_i32 s72, s72, s30
	s_cmpk_lt_i32 s72, 0x400
	s_cbranch_scc0 .LBB0_315

; #define LAS __attribute__((address_space(3)))
; __device__ __forceinline__ int crow(int r, int h) { return (r & 3) + 8 * (r >> 2) + 4 * h; }
; __device__ __forceinline__ void sb_unit(const Params& p, LAS unsigned char* lds, int b, int h, int qb) {
;     ...
;         if (lane == 0) flag[cur * 8 + wid] = done ? 1u : 0u;
;         asm volatile("s_waitcnt vmcnt(0)" ::: "memory");
;         __syncthreads();
;         const u32x4 f0 = *(const LAS u32x4*)(flag + cur * 8), f1 = *(const LAS u32x4*)(flag + cur * 8 + 4);
;         if ((f0.x & f0.y & f0.z & f0.w & f1.x & f1.y & f1.z & f1.w) != 0u) break;
;     }
;     float gn[4];
; #pragma unroll
;     for (int db = 0; db < 4; ++db) gn[db] = p.sb_gain[32 * db + c];
; #pragma unroll
;     for (int r = 0; r < 16; ++r) {
;         const int qr = crow(r, hh);
;         float ss = 0.f;
; #pragma unroll
;         for (int db = 0; db < 4; ++db) ss += O[db][r] * O[db][r];
; #pragma unroll
;         for (int off = 1; off < 32; off <<= 1) ss += __shfl_xor(ss, off);
;         const float rs = 1.0f / sqrtf(ss * (1.0f / 128.0f) + EPS);
.LBB0_327:
	s_lshl_b32 s10, s10, 5
	s_and_saveexec_b64 s[14:15], s[4:5]
	s_add_i32 s34, s48, s10
	v_cndmask_b32_e64 v64, 0, 1, s[8:9]
	v_mov_b32_e32 v65, s34
	ds_write_b32 v65, v64
	s_or_b64 exec, exec, s[14:15]
	s_add_i32 s10, s10, 0
	s_add_i32 s10, s10, 0x10400
	v_mov_b32_e32 v68, s10
	s_waitcnt vmcnt(0)
	s_waitcnt vmcnt(0) lgkmcnt(0)
	s_barrier
	ds_read_b128 v[64:67], v68
	ds_read_b128 v[68:71], v68 offset:16
	s_add_i32 s10, s23, -1
	s_cmp_lg_u32 s23, 0
	s_cselect_b64 s[14:15], -1, 0
	s_waitcnt lgkmcnt(1)
	v_and_b32_e32 v64, v64, v65
	v_and_b32_e32 v64, v64, v66
	v_and_b32_e32 v64, v64, v67
	s_waitcnt lgkmcnt(0)
	v_and_b32_e32 v64, v64, v68
	v_and_b32_e32 v64, v64, v69
	v_and_b32_e32 v64, v64, v70
	v_and_b32_e32 v64, v64, v71
	v_cmp_eq_u32_e32 vcc, 0, v64
	s_and_b64 s[14:15], s[14:15], vcc
	v_add_u32_e32 v191, 64, v191
	s_and_b64 vcc, exec, s[14:15]
	s_cbranch_vccnz .LBB0_323
	v_and_b32_e32 v224, 31, v163
	v_lshrrev_b32_e32 v225, 5, v163
	v_xor_b32_e32 v226, 16, v163
	v_xor_b32_e32 v227, 8, v163
	v_xor_b32_e32 v228, 4, v163
	v_xor_b32_e32 v229, 2, v163
	v_xor_b32_e32 v230, 1, v163
	v_lshlrev_b32_e32 v226, 2, v226
	v_lshlrev_b32_e32 v227, 2, v227
	v_lshlrev_b32_e32 v228, 2, v228
	v_lshlrev_b32_e32 v229, 2, v229
	v_lshlrev_b32_e32 v230, 2, v230
	v_and_b32_e32 v135, 16, v163
	v_cmp_ne_u32_e64 s[0:1], 0, v135
	v_and_b32_e32 v135, 8, v163
	v_cmp_ne_u32_e64 s[4:5], 0, v135
	v_and_b32_e32 v135, 4, v163
	v_cmp_ne_u32_e64 s[98:99], 0, v135
	v_and_b32_e32 v135, 2, v163
	v_cmp_ne_u32_e64 s[100:101], 0, v135
	v_lshlrev_b32_e32 v231, 2, v224
	global_load_dword v196, v231, s[56:57] offset:0
	global_load_dword v198, v231, s[56:57] offset:128
	global_load_dword v200, v231, s[56:57] offset:256
	global_load_dword v202, v231, s[56:57] offset:384
	v_mov_b32_e32 v131, 0x358637bd
	v_mov_b32_e32 v132, 0x260
	v_pk_mul_f32 v[64:65], v[0:1], v[0:1]
	v_pk_fma_f32 v[64:65], v[48:49], v[48:49], v[64:65]
	v_pk_fma_f32 v[64:65], v[32:33], v[32:33], v[64:65]
	v_pk_fma_f32 v[64:65], v[16:17], v[16:17], v[64:65]
	v_pk_mul_f32 v[66:67], v[2:3], v[2:3]
	v_pk_fma_f32 v[66:67], v[50:51], v[50:51], v[66:67]
	v_pk_fma_f32 v[66:67], v[34:35], v[34:35], v[66:67]
	v_pk_fma_f32 v[66:67], v[18:19], v[18:19], v[66:67]
	v_pk_mul_f32 v[68:69], v[4:5], v[4:5]
	v_pk_fma_f32 v[68:69], v[52:53], v[52:53], v[68:69]
	v_pk_fma_f32 v[68:69], v[36:37], v[36:37], v[68:69]
	v_pk_fma_f32 v[68:69], v[20:21], v[20:21], v[68:69]
	v_pk_mul_f32 v[70:71], v[6:7], v[6:7]
	v_pk_fma_f32 v[70:71], v[54:55], v[54:55], v[70:71]
	v_pk_fma_f32 v[70:71], v[38:39], v[38:39], v[70:71]
	v_pk_fma_f32 v[70:71], v[22:23], v[22:23], v[70:71]
	v_pk_mul_f32 v[72:73], v[8:9], v[8:9]
	v_pk_fma_f32 v[72:73], v[56:57], v[56:57], v[72:73]
	v_pk_fma_f32 v[72:73], v[40:41], v[40:41], v[72:73]
	v_pk_fma_f32 v[72:73], v[24:25], v[24:25], v[72:73]
	v_pk_mul_f32 v[74:75], v[10:11], v[10:11]
	v_pk_fma_f32 v[74:75], v[58:59], v[58:59], v[74:75]
	v_pk_fma_f32 v[74:75], v[42:43], v[42:43], v[74:75]
	v_pk_fma_f32 v[74:75], v[26:27], v[26:27], v[74:75]
	v_pk_mul_f32 v[76:77], v[12:13], v[12:13]
	v_pk_fma_f32 v[76:77], v[60:61], v[60:61], v[76:77]
	v_pk_fma_f32 v[76:77], v[44:45], v[44:45], v[76:77]
	v_pk_fma_f32 v[76:77], v[28:29], v[28:29], v[76:77]
	v_pk_mul_f32 v[78:79], v[14:15], v[14:15]
	v_pk_fma_f32 v[78:79], v[62:63], v[62:63], v[78:79]
	v_pk_fma_f32 v[78:79], v[46:47], v[46:47], v[78:79]
	v_pk_fma_f32 v[78:79], v[30:31], v[30:31], v[78:79]
	v_cndmask_b32_e64 v80, v64, v72, s[0:1]
	v_cndmask_b32_e64 v88, v72, v64, s[0:1]
	v_cndmask_b32_e64 v81, v65, v73, s[0:1]
	v_cndmask_b32_e64 v89, v73, v65, s[0:1]
	v_cndmask_b32_e64 v82, v66, v74, s[0:1]
	v_cndmask_b32_e64 v90, v74, v66, s[0:1]
	v_cndmask_b32_e64 v83, v67, v75, s[0:1]
	v_cndmask_b32_e64 v91, v75, v67, s[0:1]
	v_cndmask_b32_e64 v84, v68, v76, s[0:1]
	v_cndmask_b32_e64 v92, v76, v68, s[0:1]
	v_cndmask_b32_e64 v85, v69, v77, s[0:1]
	v_cndmask_b32_e64 v93, v77, v69, s[0:1]
	v_cndmask_b32_e64 v86, v70, v78, s[0:1]
	v_cndmask_b32_e64 v94, v78, v70, s[0:1]
	v_cndmask_b32_e64 v87, v71, v79, s[0:1]
	v_cndmask_b32_e64 v95, v79, v71, s[0:1]
	ds_bpermute_b32 v96, v226, v88
	ds_bpermute_b32 v97, v226, v89
	ds_bpermute_b32 v98, v226, v90
	ds_bpermute_b32 v99, v226, v91
	ds_bpermute_b32 v100, v226, v92
	ds_bpermute_b32 v101, v226, v93
	ds_bpermute_b32 v102, v226, v94
	ds_bpermute_b32 v103, v226, v95
	s_waitcnt lgkmcnt(0)
	v_add_f32_e32 v80, v80, v96
	v_add_f32_e32 v81, v81, v97
	v_add_f32_e32 v82, v82, v98
	v_add_f32_e32 v83, v83, v99
	v_add_f32_e32 v84, v84, v100
	v_add_f32_e32 v85, v85, v101
	v_add_f32_e32 v86, v86, v102
	v_add_f32_e32 v87, v87, v103
	v_cndmask_b32_e64 v104, v80, v84, s[4:5]
	v_cndmask_b32_e64 v108, v84, v80, s[4:5]
	v_cndmask_b32_e64 v105, v81, v85, s[4:5]
	v_cndmask_b32_e64 v109, v85, v81, s[4:5]
	v_cndmask_b32_e64 v106, v82, v86, s[4:5]
	v_cndmask_b32_e64 v110, v86, v82, s[4:5]
	v_cndmask_b32_e64 v107, v83, v87, s[4:5]
	v_cndmask_b32_e64 v111, v87, v83, s[4:5]
	ds_bpermute_b32 v112, v227, v108
	ds_bpermute_b32 v113, v227, v109
	ds_bpermute_b32 v114, v227, v110
	ds_bpermute_b32 v115, v227, v111
	s_waitcnt lgkmcnt(0)
	v_add_f32_e32 v104, v104, v112
	v_add_f32_e32 v105, v105, v113
	v_add_f32_e32 v106, v106, v114
	v_add_f32_e32 v107, v107, v115
	v_cndmask_b32_e64 v116, v104, v106, s[98:99]
	v_cndmask_b32_e64 v118, v106, v104, s[98:99]
	v_cndmask_b32_e64 v117, v105, v107, s[98:99]
	v_cndmask_b32_e64 v119, v107, v105, s[98:99]
	ds_bpermute_b32 v120, v228, v118
	ds_bpermute_b32 v121, v228, v119
	s_waitcnt lgkmcnt(0)
	v_add_f32_e32 v116, v116, v120
	v_add_f32_e32 v117, v117, v121
	v_cndmask_b32_e64 v122, v116, v117, s[100:101]
	v_cndmask_b32_e64 v123, v117, v116, s[100:101]
	ds_bpermute_b32 v124, v229, v123
	s_waitcnt lgkmcnt(0)
; __device__ __forceinline__ unsigned cvtpk(float lo, float hi) { f32x2_t v = {lo, hi}; bf16x2_t b = __builtin_convertvector(v, bf16x2_t); return __builtin_bit_cast(unsigned, b); }
; __device__ __forceinline__ int crow(int r, int h) { return (r & 3) + 8 * (r >> 2) + 4 * h; }
; __device__ __forceinline__ void sb_unit(const Params& p, LAS unsigned char* lds, int b, int h, int qb) {
;     ...
;     for (int r = 0; r < 16; ++r) {
;         const int qr = crow(r, hh);
;         float ss = 0.f;
; #pragma unroll
;         for (int db = 0; db < 4; ++db) ss += O[db][r] * O[db][r];
; #pragma unroll
;         for (int off = 1; off < 32; off <<= 1) ss += __shfl_xor(ss, off);
;         const float rs = 1.0f / sqrtf(ss * (1.0f / 128.0f) + EPS);
;         bf16_t* op = AO + (rowbase + q0 + qr) * DM + 1024 + h * 128 + c;
; #pragma unroll
;         for (int db = 0; db < 4; ++db) op[32 * db] = (bf16_t)(cvtpk(O[db][r] * rs * gn[db], 0.f) & 0xffffu);
	v_add_f32_e32 v122, v122, v124
	ds_bpermute_b32 v124, v230, v122
	s_waitcnt lgkmcnt(0)
	v_add_f32_e32 v122, v122, v124
	v_fmamk_f32 v122, v122, 0x3c000000, v131
	v_mul_f32_e32 v126, 0x4f800000, v122
	v_cmp_gt_f32_e32 vcc, 0xf800000, v122
	s_nop 1
	v_cndmask_b32_e32 v122, v122, v126, vcc
	v_sqrt_f32_e32 v126, v122
	s_nop 0
	v_add_u32_e32 v127, -1, v126
	v_add_u32_e32 v128, 1, v126
	v_fma_f32 v129, -v127, v126, v122
	v_fma_f32 v130, -v128, v126, v122
	v_cmp_ge_f32_e64 s[0:1], 0, v129
	s_nop 1
	v_cndmask_b32_e64 v126, v126, v127, s[0:1]
	v_cmp_lt_f32_e64 s[0:1], 0, v130
	s_nop 1
	v_cndmask_b32_e64 v126, v126, v128, s[0:1]
	v_mul_f32_e32 v127, 0x37800000, v126
	v_cndmask_b32_e32 v126, v126, v127, vcc
	v_cmp_class_f32_e32 vcc, v122, v132
	s_nop 1
	v_cndmask_b32_e32 v122, v126, v122, vcc
	v_div_scale_f32 v126, s[0:1], v122, v122, 1.0
	v_rcp_f32_e32 v128, v126
	v_div_scale_f32 v127, vcc, 1.0, v122, 1.0
	v_fma_f32 v129, -v126, v128, 1.0
	v_fmac_f32_e32 v128, v129, v128
	v_mul_f32_e32 v129, v127, v128
	v_fma_f32 v130, -v126, v129, v127
	v_fmac_f32_e32 v129, v130, v128
	v_fma_f32 v126, -v126, v129, v127
	v_div_fmas_f32 v126, v126, v128, v129
	v_div_fixup_f32 v123, v126, v122, 1.0
	v_readfirstlane_b32 s1, v162
	s_nop 3
	s_lshr_b32 s1, s1, 6
	s_lshl_b32 s1, s1, 7
	s_add_u32 s1, s1, 0x10800
	v_and_b32_e32 v135, 30, v224
	v_lshlrev_b32_e32 v135, 1, v135
	v_lshl_add_u32 v135, v225, 6, v135
	v_add_u32_e32 v133, s1, v135
	v_lshlrev_b32_e32 v134, 6, v225
	v_add_u32_e32 v134, s1, v134
	ds_write_b32 v133, v123
	s_waitcnt lgkmcnt(0)
	ds_read_b128 v[176:179], v134
	ds_read_b128 v[180:183], v134 offset:16
	ds_read_b128 v[184:187], v134 offset:32
	ds_read_b128 v[192:195], v134 offset:48
	s_and_b32 s0, s16, 3
	s_lshr_b32 s1, s16, 8
	s_xor_b32 s4, s0, 7
	s_or_b32 s5, s0, 8
	s_xor_b32 s10, s0, 15
	s_cmp_eq_u32 s1, 1
	s_cselect_b32 s0, s4, s0
	s_cmp_eq_u32 s1, 2
	s_cselect_b32 s0, s5, s0
	s_cmp_eq_u32 s1, 3
	s_cselect_b32 s0, s10, s0
	v_readfirstlane_b32 s1, v162
	s_nop 3
	s_lshr_b32 s1, s1, 6
	s_lshl_b32 s0, s0, 8
	s_lshl_b32 s1, s1, 5
	s_add_u32 s0, s0, s1
	s_bfe_u32 s1, s16, 0x30005
	s_lshl_b32 s1, s1, 12
	s_add_u32 s0, s0, s1
	s_lshl_b32 s4, s0, 12
	s_bfe_u32 s1, s16, 0x30002
	s_lshl_b32 s1, s1, 8
	s_add_u32 s4, s4, s1
	s_add_u32 s4, s4, 0x800
	s_add_u32 s0, s28, 0x2e000000
	s_addc_u32 s1, s29, 0
	s_add_u32 s0, s0, s4
	s_addc_u32 s1, s1, 0
	s_add_u32 s4, s0, 0x10000
	s_addc_u32 s5, s1, 0
	v_readfirstlane_b32 s10, v162
	s_nop 3
	s_lshr_b32 s10, s10, 6
	s_lshl_b32 s10, s10, 12
	s_add_u32 s10, s10, 0x11000
	v_lshlrev_b32_e32 v135, 9, v225
	v_lshl_add_u32 v135, v224, 1, v135
	v_add_u32_e32 v204, s10, v135
	v_lshlrev_b32_e32 v135, 4, v163
	v_add_u32_e32 v205, s10, v135
	v_lshrrev_b32_e32 v135, 3, v163
	v_lshlrev_b32_e32 v135, 12, v135
	v_and_b32_e32 v206, 7, v163
	v_lshl_add_u32 v206, v206, 4, v135
	v_add_u32_e32 v207, 0x8000, v206
	s_waitcnt vmcnt(0) lgkmcnt(0)
	v_pk_mul_f32 v[212:213], v[0:1], v[176:177]
	v_pk_mul_f32 v[212:213], v[212:213], v[196:197] op_sel_hi:[1,0]
	v_cvt_pk_bf16_f32 v216, v212, v213
	ds_write_b16 v204, v216
	ds_write_b16_d16_hi v204, v216 offset:128
	v_pk_mul_f32 v[214:215], v[2:3], v[178:179]
	v_pk_mul_f32 v[214:215], v[214:215], v[196:197] op_sel_hi:[1,0]
	v_cvt_pk_bf16_f32 v217, v214, v215
	ds_write_b16 v204, v217 offset:256
	ds_write_b16_d16_hi v204, v217 offset:384
	v_pk_mul_f32 v[212:213], v[4:5], v[180:181]
	v_pk_mul_f32 v[212:213], v[212:213], v[196:197] op_sel_hi:[1,0]
	v_cvt_pk_bf16_f32 v218, v212, v213
	ds_write_b16 v204, v218 offset:1024
	ds_write_b16_d16_hi v204, v218 offset:1152
	v_pk_mul_f32 v[214:215], v[6:7], v[182:183]
	v_pk_mul_f32 v[214:215], v[214:215], v[196:197] op_sel_hi:[1,0]
	v_cvt_pk_bf16_f32 v219, v214, v215
	ds_write_b16 v204, v219 offset:1280
	ds_write_b16_d16_hi v204, v219 offset:1408
	v_pk_mul_f32 v[212:213], v[8:9], v[184:185]
	v_pk_mul_f32 v[212:213], v[212:213], v[196:197] op_sel_hi:[1,0]
	v_cvt_pk_bf16_f32 v220, v212, v213
	ds_write_b16 v204, v220 offset:2048
	ds_write_b16_d16_hi v204, v220 offset:2176
	v_pk_mul_f32 v[214:215], v[10:11], v[186:187]
	v_pk_mul_f32 v[214:215], v[214:215], v[196:197] op_sel_hi:[1,0]
	v_cvt_pk_bf16_f32 v221, v214, v215
	ds_write_b16 v204, v221 offset:2304
	ds_write_b16_d16_hi v204, v221 offset:2432
	v_pk_mul_f32 v[212:213], v[12:13], v[192:193]
	v_pk_mul_f32 v[212:213], v[212:213], v[196:197] op_sel_hi:[1,0]
	v_cvt_pk_bf16_f32 v222, v212, v213
	ds_write_b16 v204, v222 offset:3072
	ds_write_b16_d16_hi v204, v222 offset:3200
	v_pk_mul_f32 v[214:215], v[14:15], v[194:195]
	v_pk_mul_f32 v[214:215], v[214:215], v[196:197] op_sel_hi:[1,0]
	v_cvt_pk_bf16_f32 v223, v214, v215
	ds_write_b16 v204, v223 offset:3328
	ds_write_b16_d16_hi v204, v223 offset:3456
	v_pk_mul_f32 v[212:213], v[48:49], v[176:177]
	v_pk_mul_f32 v[212:213], v[212:213], v[198:199] op_sel_hi:[1,0]
	v_cvt_pk_bf16_f32 v216, v212, v213
	ds_write_b16 v204, v216 offset:64
	ds_write_b16_d16_hi v204, v216 offset:192
	v_pk_mul_f32 v[214:215], v[50:51], v[178:179]
	v_pk_mul_f32 v[214:215], v[214:215], v[198:199] op_sel_hi:[1,0]
	v_cvt_pk_bf16_f32 v217, v214, v215
	ds_write_b16 v204, v217 offset:320
	ds_write_b16_d16_hi v204, v217 offset:448
	v_pk_mul_f32 v[212:213], v[52:53], v[180:181]
	v_pk_mul_f32 v[212:213], v[212:213], v[198:199] op_sel_hi:[1,0]
	v_cvt_pk_bf16_f32 v218, v212, v213
	ds_write_b16 v204, v218 offset:1088
	ds_write_b16_d16_hi v204, v218 offset:1216
	v_pk_mul_f32 v[214:215], v[54:55], v[182:183]
	v_pk_mul_f32 v[214:215], v[214:215], v[198:199] op_sel_hi:[1,0]
	v_cvt_pk_bf16_f32 v219, v214, v215
	ds_write_b16 v204, v219 offset:1344
	ds_write_b16_d16_hi v204, v219 offset:1472
	v_pk_mul_f32 v[212:213], v[56:57], v[184:185]
	v_pk_mul_f32 v[212:213], v[212:213], v[198:199] op_sel_hi:[1,0]
	v_cvt_pk_bf16_f32 v220, v212, v213
	ds_write_b16 v204, v220 offset:2112
	ds_write_b16_d16_hi v204, v220 offset:2240
	v_pk_mul_f32 v[214:215], v[58:59], v[186:187]
	v_pk_mul_f32 v[214:215], v[214:215], v[198:199] op_sel_hi:[1,0]
	v_cvt_pk_bf16_f32 v221, v214, v215
	ds_write_b16 v204, v221 offset:2368
	ds_write_b16_d16_hi v204, v221 offset:2496
	v_pk_mul_f32 v[212:213], v[60:61], v[192:193]
	v_pk_mul_f32 v[212:213], v[212:213], v[198:199] op_sel_hi:[1,0]
	v_cvt_pk_bf16_f32 v222, v212, v213
	ds_write_b16 v204, v222 offset:3136
	ds_write_b16_d16_hi v204, v222 offset:3264
	v_pk_mul_f32 v[214:215], v[62:63], v[194:195]
	v_pk_mul_f32 v[214:215], v[214:215], v[198:199] op_sel_hi:[1,0]
	v_cvt_pk_bf16_f32 v223, v214, v215
	ds_write_b16 v204, v223 offset:3392
	ds_write_b16_d16_hi v204, v223 offset:3520
	ds_read_b128 v[0:3], v205
	ds_read_b128 v[4:7], v205 offset:1024
	ds_read_b128 v[8:11], v205 offset:2048
	ds_read_b128 v[12:15], v205 offset:3072
	s_waitcnt lgkmcnt(3)
; __device__ __forceinline__ unsigned cvtpk(float lo, float hi) { f32x2_t v = {lo, hi}; bf16x2_t b = __builtin_convertvector(v, bf16x2_t); return __builtin_bit_cast(unsigned, b); }
; __device__ __forceinline__ int crow(int r, int h) { return (r & 3) + 8 * (r >> 2) + 4 * h; }
; __device__ __forceinline__ void sb_unit(const Params& p, LAS unsigned char* lds, int b, int h, int qb) {
;     ...
;     for (int r = 0; r < 16; ++r) {
;         const int qr = crow(r, hh);
;         float ss = 0.f;
; #pragma unroll
;         for (int db = 0; db < 4; ++db) ss += O[db][r] * O[db][r];
; #pragma unroll
;         for (int off = 1; off < 32; off <<= 1) ss += __shfl_xor(ss, off);
;         const float rs = 1.0f / sqrtf(ss * (1.0f / 128.0f) + EPS);
;         bf16_t* op = AO + (rowbase + q0 + qr) * DM + 1024 + h * 128 + c;
; #pragma unroll
;         for (int db = 0; db < 4; ++db) op[32 * db] = (bf16_t)(cvtpk(O[db][r] * rs * gn[db], 0.f) & 0xffffu);
;     }
;     asm volatile("s_waitcnt vmcnt(0)" ::: "memory");
;     __syncthreads();
	global_store_dwordx4 v206, v[0:3], s[0:1]
	s_waitcnt lgkmcnt(2)
	global_store_dwordx4 v207, v[4:7], s[0:1]
	s_waitcnt lgkmcnt(1)
	global_store_dwordx4 v206, v[8:11], s[4:5]
	s_waitcnt lgkmcnt(0)
	global_store_dwordx4 v207, v[12:15], s[4:5]
	v_pk_mul_f32 v[212:213], v[32:33], v[176:177]
	v_pk_mul_f32 v[212:213], v[212:213], v[200:201] op_sel_hi:[1,0]
	v_cvt_pk_bf16_f32 v216, v212, v213
	ds_write_b16 v204, v216
	ds_write_b16_d16_hi v204, v216 offset:128
	v_pk_mul_f32 v[214:215], v[34:35], v[178:179]
	v_pk_mul_f32 v[214:215], v[214:215], v[200:201] op_sel_hi:[1,0]
	v_cvt_pk_bf16_f32 v217, v214, v215
	ds_write_b16 v204, v217 offset:256
	ds_write_b16_d16_hi v204, v217 offset:384
	v_pk_mul_f32 v[212:213], v[36:37], v[180:181]
	v_pk_mul_f32 v[212:213], v[212:213], v[200:201] op_sel_hi:[1,0]
	v_cvt_pk_bf16_f32 v218, v212, v213
	ds_write_b16 v204, v218 offset:1024
	ds_write_b16_d16_hi v204, v218 offset:1152
	v_pk_mul_f32 v[214:215], v[38:39], v[182:183]
	v_pk_mul_f32 v[214:215], v[214:215], v[200:201] op_sel_hi:[1,0]
	v_cvt_pk_bf16_f32 v219, v214, v215
	ds_write_b16 v204, v219 offset:1280
	ds_write_b16_d16_hi v204, v219 offset:1408
	v_pk_mul_f32 v[212:213], v[40:41], v[184:185]
	v_pk_mul_f32 v[212:213], v[212:213], v[200:201] op_sel_hi:[1,0]
	v_cvt_pk_bf16_f32 v220, v212, v213
	ds_write_b16 v204, v220 offset:2048
	ds_write_b16_d16_hi v204, v220 offset:2176
	v_pk_mul_f32 v[214:215], v[42:43], v[186:187]
	v_pk_mul_f32 v[214:215], v[214:215], v[200:201] op_sel_hi:[1,0]
	v_cvt_pk_bf16_f32 v221, v214, v215
	ds_write_b16 v204, v221 offset:2304
	ds_write_b16_d16_hi v204, v221 offset:2432
	v_pk_mul_f32 v[212:213], v[44:45], v[192:193]
	v_pk_mul_f32 v[212:213], v[212:213], v[200:201] op_sel_hi:[1,0]
	v_cvt_pk_bf16_f32 v222, v212, v213
	ds_write_b16 v204, v222 offset:3072
	ds_write_b16_d16_hi v204, v222 offset:3200
	v_pk_mul_f32 v[214:215], v[46:47], v[194:195]
	v_pk_mul_f32 v[214:215], v[214:215], v[200:201] op_sel_hi:[1,0]
	v_cvt_pk_bf16_f32 v223, v214, v215
	ds_write_b16 v204, v223 offset:3328
	ds_write_b16_d16_hi v204, v223 offset:3456
	v_pk_mul_f32 v[212:213], v[16:17], v[176:177]
	v_pk_mul_f32 v[212:213], v[212:213], v[202:203] op_sel_hi:[1,0]
	v_cvt_pk_bf16_f32 v216, v212, v213
	ds_write_b16 v204, v216 offset:64
	ds_write_b16_d16_hi v204, v216 offset:192
	v_pk_mul_f32 v[214:215], v[18:19], v[178:179]
	v_pk_mul_f32 v[214:215], v[214:215], v[202:203] op_sel_hi:[1,0]
	v_cvt_pk_bf16_f32 v217, v214, v215
	ds_write_b16 v204, v217 offset:320
	ds_write_b16_d16_hi v204, v217 offset:448
	v_pk_mul_f32 v[212:213], v[20:21], v[180:181]
	v_pk_mul_f32 v[212:213], v[212:213], v[202:203] op_sel_hi:[1,0]
	v_cvt_pk_bf16_f32 v218, v212, v213
	ds_write_b16 v204, v218 offset:1088
	ds_write_b16_d16_hi v204, v218 offset:1216
	v_pk_mul_f32 v[214:215], v[22:23], v[182:183]
	v_pk_mul_f32 v[214:215], v[214:215], v[202:203] op_sel_hi:[1,0]
	v_cvt_pk_bf16_f32 v219, v214, v215
	ds_write_b16 v204, v219 offset:1344
	ds_write_b16_d16_hi v204, v219 offset:1472
	v_pk_mul_f32 v[212:213], v[24:25], v[184:185]
	v_pk_mul_f32 v[212:213], v[212:213], v[202:203] op_sel_hi:[1,0]
	v_cvt_pk_bf16_f32 v220, v212, v213
	ds_write_b16 v204, v220 offset:2112
	ds_write_b16_d16_hi v204, v220 offset:2240
	v_pk_mul_f32 v[214:215], v[26:27], v[186:187]
	v_pk_mul_f32 v[214:215], v[214:215], v[202:203] op_sel_hi:[1,0]
	v_cvt_pk_bf16_f32 v221, v214, v215
	ds_write_b16 v204, v221 offset:2368
	ds_write_b16_d16_hi v204, v221 offset:2496
	v_pk_mul_f32 v[212:213], v[28:29], v[192:193]
	v_pk_mul_f32 v[212:213], v[212:213], v[202:203] op_sel_hi:[1,0]
	v_cvt_pk_bf16_f32 v222, v212, v213
	ds_write_b16 v204, v222 offset:3136
	ds_write_b16_d16_hi v204, v222 offset:3264
	v_pk_mul_f32 v[214:215], v[30:31], v[194:195]
	v_pk_mul_f32 v[214:215], v[214:215], v[202:203] op_sel_hi:[1,0]
	v_cvt_pk_bf16_f32 v223, v214, v215
	ds_write_b16 v204, v223 offset:3392
	ds_write_b16_d16_hi v204, v223 offset:3520
	ds_read_b128 v[32:35], v205
	ds_read_b128 v[36:39], v205 offset:1024
	ds_read_b128 v[40:43], v205 offset:2048
	ds_read_b128 v[44:47], v205 offset:3072
	s_waitcnt lgkmcnt(3)
	global_store_dwordx4 v206, v[32:35], s[0:1] offset:128
	s_waitcnt lgkmcnt(2)
	global_store_dwordx4 v207, v[36:39], s[0:1] offset:128
	s_waitcnt lgkmcnt(1)
	global_store_dwordx4 v206, v[40:43], s[4:5] offset:128
	s_waitcnt lgkmcnt(0)
	global_store_dwordx4 v207, v[44:47], s[4:5] offset:128
	s_waitcnt vmcnt(0)
	s_barrier
	s_add_i32 s16, s16, s30
	s_cmpk_lt_i32 s16, 0x400
	s_cbranch_scc1 .LBB0_316
